# baseline (speedup 1.0000x reference)
; __device__ __forceinline__ void gemm_phase(KP p, char* shmc, const u16* __restrict__ A,
;                                            const u16* __restrict__ Bt, const int N, const int K, const int mode,
;                                            const float* __restrict__ xin, const float resw) {
;     ...
;     const int ntix = tix + gridDim.x;
;     int nbrow = 0, nbcol = 0, npn = 0;
;     if (ntix < nwg) {
;       TILE_MAP(ntix, nbrow, nbcol, npn);
.LBB0_47:
	v_mov_b32_e32 v217, v210
	s_nop 0
	v_ashrrev_i32_e32 v0, 8, v217
	s_add_i32 s66, s66, s3
	s_cmp_ge_i32 s66, s51
	s_cselect_b64 s[6:7], -1, 0
	s_mov_b32 s26, 0
	s_and_b64 vcc, exec, s[6:7]
	s_mov_b32 s45, 0
	s_mov_b32 s44, 0
	s_cbranch_vccnz .Lmy_nomap
	s_ashr_i32 s8, s66, 31
	s_lshr_b32 s8, s8, 29
	s_add_i32 s8, s66, s8
	s_ashr_i32 s9, s8, 3
	s_and_b32 s8, s8, -8
	s_sub_i32 s8, s66, s8
	s_lshr_b32 s26, s8, 31
	s_or_b32 s26, s26, s68
	s_mul_i32 s8, s26, s8
	s_add_i32 s8, s8, s9
	s_abs_i32 s26, s8
	s_mul_hi_u32 s27, s26, s69
	s_mul_i32 s36, s27, s81
	s_sub_i32 s26, s26, s36
	s_ashr_i32 s9, s8, 31
	s_add_i32 s36, s27, 1
	s_sub_i32 s37, s26, s81
	s_cmp_ge_u32 s26, s81
	s_cselect_b32 s27, s36, s27
	s_cselect_b32 s26, s37, s26
	s_add_i32 s36, s27, 1
	s_cmp_ge_u32 s26, s81
	s_cselect_b32 s26, s36, s27
	s_xor_b32 s26, s26, s9
	s_sub_i32 s9, s26, s9
	s_lshl_b32 s26, s9, 2
	s_sub_i32 s27, 64, s26
	s_min_i32 s27, s27, 4
	s_abs_i32 s36, s27
	v_cvt_f32_u32_e32 v130, s36
	s_sub_i32 s38, 0, s36
	s_mul_i32 s9, s9, s81
	s_sub_i32 s8, s8, s9
	v_rcp_iflag_f32_e32 v130, v130
	s_abs_i32 s37, s8
	s_xor_b32 s9, s8, s27
	s_ashr_i32 s9, s9, 31
	v_mul_f32_e32 v130, 0x4f7ffffe, v130
	v_cvt_u32_f32_e32 v130, v130
	s_nop 0
	v_readfirstlane_b32 s39, v130
	s_mul_i32 s38, s38, s39
	s_mul_hi_u32 s38, s39, s38
	s_add_i32 s39, s39, s38
	s_mul_hi_u32 s38, s37, s39
	s_mul_i32 s39, s38, s36
	s_sub_i32 s37, s37, s39
	s_add_i32 s39, s38, 1
	s_sub_i32 s40, s37, s36
	s_cmp_ge_u32 s37, s36
	s_cselect_b32 s38, s39, s38
	s_cselect_b32 s37, s40, s37
	s_add_i32 s39, s38, 1
	s_cmp_ge_u32 s37, s36
	s_cselect_b32 s36, s39, s38
	s_xor_b32 s36, s36, s9
	s_sub_i32 s44, s36, s9
	s_mul_i32 s9, s44, s27
	s_sub_i32 s8, s8, s9
	s_add_i32 s8, s8, s26
	s_lshl_b32 s45, s44, 8
	s_lshl_b32 s26, s8, 8
